# on top of the S3 batch-read version: record-store acks not waited inside the kk loop (per-wave-class vmcnt), next-unit rows loaded straight into their staging registers
# baseline (speedup 1.0000x reference)
.LBB0_500:
	v_lshlrev_b32_e32 v20, 16, v114
	v_and_b32_e32 v21, 0xffff0000, v114
	v_lshlrev_b32_e32 v34, 16, v118
	v_and_b32_e32 v35, 0xffff0000, v118
	v_pk_fma_f32 v[20:21], v[6:7], v[20:21], 0 op_sel_hi:[1,1,0]
	v_lshlrev_b32_e32 v42, 16, v122
	v_and_b32_e32 v43, 0xffff0000, v122
	v_pk_fma_f32 v[20:21], v[10:11], v[34:35], v[20:21]
	v_lshlrev_b32_e32 v50, 16, v126
	v_and_b32_e32 v51, 0xffff0000, v126
	v_pk_fma_f32 v[20:21], v[98:99], v[42:43], v[20:21]
	v_lshlrev_b32_e32 v32, 16, v119
	v_pk_fma_f32 v[20:21], v[106:107], v[50:51], v[20:21]
	v_and_b32_e32 v33, 0xffff0000, v119
	v_mul_f32_e32 v22, 0xbfb8aa3b, v20
	v_mul_f32_e32 v23, 0xbfb8aa3b, v21
	v_exp_f32_e32 v22, v22
	v_exp_f32_e32 v23, v23
	v_lshlrev_b32_e32 v40, 16, v123
	v_and_b32_e32 v41, 0xffff0000, v123
	v_add_f32_e32 v22, 1.0, v22
	v_add_f32_e32 v23, 1.0, v23
	v_rcp_f32_e32 v22, v22
	v_rcp_f32_e32 v23, v23
	v_lshlrev_b32_e32 v46, 16, v127
	v_and_b32_e32 v47, 0xffff0000, v127
	v_lshlrev_b32_e32 v52, 16, v116
	v_pk_mul_f32 v[20:21], v[20:21], v[22:23]
	v_lshlrev_b32_e32 v22, 16, v115
	v_and_b32_e32 v23, 0xffff0000, v115
	v_pk_fma_f32 v[22:23], v[8:9], v[22:23], 0 op_sel_hi:[1,1,0]
	v_and_b32_e32 v53, 0xffff0000, v116
	v_pk_fma_f32 v[22:23], v[12:13], v[32:33], v[22:23]
	v_lshlrev_b32_e32 v30, 16, v120
	v_pk_fma_f32 v[22:23], v[100:101], v[40:41], v[22:23]
	v_and_b32_e32 v31, 0xffff0000, v120
	v_pk_fma_f32 v[22:23], v[108:109], v[46:47], v[22:23]
	v_pk_fma_f32 v[52:53], v[2:3], v[52:53], 0 op_sel_hi:[1,1,0]
	v_mul_f32_e32 v24, 0xbfb8aa3b, v22
	v_exp_f32_e32 v26, v24
	v_mul_f32_e32 v24, 0xbfb8aa3b, v23
	v_exp_f32_e32 v27, v24
	v_lshlrev_b32_e32 v38, 16, v124
	v_and_b32_e32 v39, 0xffff0000, v124
	v_pk_fma_f32 v[52:53], v[14:15], v[30:31], v[52:53]
	v_lshlrev_b32_e32 v48, 16, v128
	v_and_b32_e32 v49, 0xffff0000, v128
	v_pk_fma_f32 v[52:53], v[102:103], v[38:39], v[52:53]
	v_add_f32_e32 v26, 1.0, v26
	s_cmp_eq_u32 s64, 0
	s_cbranch_scc0 .Lp3a_s2h_skip
	s_or_b32 s98, s64, s84
	s_lshl_b32 s98, s98, 1
	v_readlane_b32 s99, v249, 49
	v_readlane_b32 s100, v249, 47
	v_readlane_b32 s101, v249, 48
	v_mov_b32_e32 v244, v1
	v_mov_b32_e32 v245, 0
	s_or_b32 s98, s98, s99
	s_lshl_b32 s98, s98, 2
	v_lshl_add_u64 v[244:245], s[88:89], 0, v[244:245]
	s_add_u32 s100, s100, s98
	s_addc_u32 s101, s101, 0
	v_lshlrev_b64 v[244:245], 8, v[244:245]
	s_nop 1
	v_lshl_add_u64 v[244:245], s[100:101], 0, v[244:245]
	s_add_u32 s100, s60, s98
	s_addc_u32 s101, s61, 0
	global_load_dword v240, v[244:245], off
	global_load_dword v241, v[244:245], off offset:128
	global_load_dword v242, v18, s[100:101]
	s_add_u32 s100, s58, s98
	s_addc_u32 s101, s59, 0
	global_load_dword v243, v18, s[100:101]

.LBB0_587:
	s_or_b32 s42, s64, s84
	s_cmp_eq_u32 s64, 0
	s_cbranch_scc1 .LBB0_612
	s_branch .LBB0_615
.LBB0_588:
	v_mov_b32_e32 v20, v18
	v_mov_b32_e32 v21, v18
	v_mov_b32_e32 v19, v18
	v_mov_b64_e32 v[24:25], v[20:21]
	v_mov_b64_e32 v[22:23], v[18:19]

.LBB0_611:
	v_mov_b64_e32 v[72:73], v[8:9]
	v_mov_b64_e32 v[68:69], v[4:5]
	v_mov_b64_e32 v[76:77], v[12:13]
	v_mov_b64_e32 v[80:81], v[16:17]
	v_mov_b64_e32 v[82:83], v[98:99]
	v_mov_b64_e32 v[86:87], v[102:103]
	v_mov_b64_e32 v[90:91], v[106:107]
	v_mov_b64_e32 v[94:95], v[110:111]
	v_mov_b64_e32 v[70:71], v[6:7]
	v_mov_b64_e32 v[66:67], v[2:3]
	v_mov_b64_e32 v[74:75], v[10:11]
	v_mov_b64_e32 v[78:79], v[14:15]
	v_mov_b64_e32 v[84:85], v[100:101]
	v_mov_b64_e32 v[88:89], v[104:105]
	v_mov_b64_e32 v[92:93], v[108:109]
	v_mov_b64_e32 v[96:97], v[112:113]
	s_or_b32 s42, s64, s84
	s_branch .LBB0_615
